# v1 plus padding: attention steady-loop head on a 64-byte boundary, later phases as v1 mod 64
# baseline (speedup 1.0000x reference)
; #define WAIT_BAR(N) asm volatile("s_waitcnt vmcnt(" #N ") lgkmcnt(0)\n\ts_barrier":::"memory")
;   #define DMA_K(t,slot) glds16(ksrc+(long)(t)*KVBLK*DM,(unsigned)__builtin_amdgcn_readfirstlane(kdst+(slot)))
;   #define DMA_V(t,slot) do{ glds16(vsrc+(long)(t)*KVBLK*DM,(unsigned)__builtin_amdgcn_readfirstlane(vdst+(slot))); glds16(vsrc+64+(long)(t)*KVBLK*DM,(unsigned)__builtin_amdgcn_readfirstlane(vdst2+(slot))); }while(0)
;   #define CMASK(P0,P1,t) do{int jb_=(t)-(NT-4); if(jb_>=0)cmask(P0,P1,jb_,qrel,hi);}while(0)
;   #define START(P0,P1) do{ resc=false; \
;     { _Pragma("unroll") for(int r=0;r<16;++r){P0[r]=fsub_s(P0[r],mhat);P1[r]=fsub_s(P1[r],mhat);} \
;       } \
;     _Pragma("unroll") for(int r=0;r<16;++r)P0[r]=__builtin_amdgcn_exp2f(P0[r]); }while(0)
;   #define ROT() do{sl_prev=sl_cur;sl_cur=sl_next;sl_next=(sl_next==(NSLOT-1)*SLOTB)?0:sl_next+SLOTB;}while(0)
;   #define CMASK(P0,P1,t) do{}while(0)
;   #define CMASK(P0,P1,t) do{int jb_=(t)-(NT-4); if(jb_>=0)cmask(P0,P1,jb_,qrel,hi);}while(0)
; template<int THRL> __device__ __forceinline__ void attn_unit(int b,int h,int qb,unsigned char*wsb,char*shm,float kmax,const int CMB,float lam){
;     ...
;   const float mhat=sqrtf(q2_)*kmax*1.004f+0.02f;
;   float l_reg=0.f;f32x16 o[2];o[0]=f32x16{};o[1]=f32x16{};f32x16 o2[2];o2[0]=f32x16{};o2[1]=f32x16{};const f32x16 negm=f32x16{};
;   const int qrel=wid*QBLK+r32;
;     ...
;   bool resc=false;
;     ...
;   f32x16 pA0,pA1,pB0,pB1;
;   int sl_prev=0,sl_cur=0,sl_next=SLOTB;
;     ...
;   DMA_K(2,2*SLOTB);
;   WAIT_BAR(4);
;   qkt(pA0,pA1,Kbase,qr,negm,r32,hi);asm volatile("s_nop 15\n\ts_nop 7":"+v"(pA0),"+v"(pA1));CMASK(pA0,pA1,0);
;   START(pA0,pA1);
;   _Pragma("unroll") for(int r=0;r<16;++r)pA1[r]=__builtin_amdgcn_exp2f(pA1[r]);
;   WAIT_BAR(0);
;   DMA_K(3,0);DMA_V(1,SLOTB);
;   ROT();
;   kload8(kf,kp0+sl_cur);
;   WAIT_BAR(3);
; __global__ void __launch_bounds__(NTHR, 2) fwd_megakernel(Args args_unused) {
;     ...
;                     const float kmax = 1.01f * sqrtf(__uint_as_float(__builtin_amdgcn_readfirstlane(__hip_atomic_load((unsigned*)(ws + WS_KMAX) + 2 * bh, __ATOMIC_RELAXED, __HIP_MEMORY_SCOPE_AGENT)))
;                                                    + __uint_as_float(__builtin_amdgcn_readfirstlane(__hip_atomic_load((unsigned*)(ws + WS_KMAX) + 2 * bh + 1, __ATOMIC_RELAXED, __HIP_MEMORY_SCOPE_AGENT))));
.LBB0_309:
	v_mov_b32_e32 v39, s6
	v_add_f32_e32 v39, s5, v39
	v_mul_f32_e32 v40, 0x4f800000, v39
	v_cmp_gt_f32_e32 vcc, s74, v39
	v_add_f32_e32 v37, v37, v38
	v_mul_f32_e32 v38, 0x4f800000, v37
	v_cndmask_b32_e32 v39, v39, v40, vcc
	v_sqrt_f32_e32 v40, v39
	s_waitcnt vmcnt(0) lgkmcnt(0)
	s_barrier
	s_cmp_lg_u32 0, -1
	s_mov_b32 s37, 0
	v_add_u32_e32 v41, -1, v40
	v_fma_f32 v42, -v41, v40, v39
	v_cmp_ge_f32_e64 s[4:5], 0, v42
	v_add_u32_e32 v42, 1, v40
	s_mov_b32 s6, 1
	v_cndmask_b32_e64 v41, v40, v41, s[4:5]
	v_fma_f32 v40, -v42, v40, v39
	v_cmp_lt_f32_e64 s[4:5], 0, v40
	s_nop 1
	v_cndmask_b32_e64 v40, v41, v42, s[4:5]
	v_mul_f32_e32 v41, 0x37800000, v40
	v_cndmask_b32_e32 v40, v40, v41, vcc
	v_cmp_class_f32_e32 vcc, v39, v237
	s_nop 1
	v_cndmask_b32_e32 v39, v40, v39, vcc
	v_cmp_gt_f32_e32 vcc, s74, v37
	v_lshlrev_b32_e32 v40, 1, v36
	v_and_b32_e32 v251, 32, v40
	v_cndmask_b32_e32 v37, v37, v38, vcc
	v_sqrt_f32_e32 v38, v37
	v_lshlrev_b32_e32 v40, 4, v36
	v_and_b32_e32 v40, 0xc0, v40
	v_lshl_or_b32 v246, v242, 8, v40
	v_add_u32_e32 v40, 0, v251
	v_add3_u32 v252, v40, v249, v246
	v_add_u32_e32 v40, -1, v38
	v_fma_f32 v41, -v40, v38, v37
	v_cmp_ge_f32_e64 s[4:5], 0, v41
	v_add_u32_e32 v41, 1, v38
	v_mul_f32_e32 v39, 0x3f8147ae, v39
	v_cndmask_b32_e64 v40, v38, v40, s[4:5]
	v_fma_f32 v38, -v41, v38, v37
	v_cmp_lt_f32_e64 s[4:5], 0, v38
	s_nop 1
	v_cndmask_b32_e64 v38, v40, v41, s[4:5]
	v_mul_f32_e32 v40, 0x37800000, v38
	v_cndmask_b32_e32 v38, v38, v40, vcc
	v_cmp_class_f32_e32 vcc, v37, v237
	s_mov_b64 s[4:5], 0x60000
	s_nop 0
	v_cndmask_b32_e32 v37, v38, v37, vcc
	v_mul_f32_e32 v37, v39, v37
	v_fmamk_f32 v247, v37, 0x3f808312, v238
	v_sub_f32_e32 v0, v0, v247
	v_sub_f32_e32 v1, v1, v247
	v_sub_f32_e32 v16, v16, v247
	v_sub_f32_e32 v17, v17, v247
	v_sub_f32_e32 v2, v2, v247
	v_sub_f32_e32 v18, v18, v247
	s_nop 0
	v_exp_f32_e32 v96, v0
	v_exp_f32_e32 v97, v1
	v_lshl_add_u64 v[0:1], v[32:33], 0, s[4:5]
	s_mov_b32 s4, m0
	s_mov_b32 m0, s3
	s_nop 0
	global_load_lds_dwordx4 v[0:1], off
	s_mov_b32 m0, s4
	s_mov_b64 s[4:5], 0x20000
	v_lshl_add_u64 v[0:1], v[34:35], 0, s[4:5]
	s_cselect_b32 s4, 0, 0
	s_add_i32 s1, s4, s1
	s_add_i32 s4, s1, 0x8000
	s_mov_b32 s5, m0
	s_mov_b32 m0, s4
	s_nop 0
	global_load_lds_dwordx4 v[0:1], off
	s_mov_b32 m0, s5
	s_mov_b64 s[4:5], 0x20080
	v_lshl_add_u64 v[0:1], v[34:35], 0, s[4:5]
	s_add_i32 s1, s1, 0xe000
	s_mov_b32 s4, m0
	s_mov_b32 m0, s1
	s_nop 0
	global_load_lds_dwordx4 v[0:1], off
	s_mov_b32 m0, s4
	ds_read_b128 v[204:207], v250 offset:8192
	ds_read_b128 v[200:203], v250 offset:8704
	ds_read_b128 v[196:199], v250 offset:10240
	ds_read_b128 v[192:195], v250 offset:10752
	ds_read_b128 v[188:191], v250 offset:12288
	ds_read_b128 v[184:187], v250 offset:12800
	ds_read_b128 v[180:183], v250 offset:14336
	ds_read_b128 v[176:179], v250 offset:14848
	v_sub_f32_e32 v3, v3, v247
	v_sub_f32_e32 v19, v19, v247
	v_sub_f32_e32 v4, v4, v247
	v_sub_f32_e32 v20, v20, v247
	v_sub_f32_e32 v5, v5, v247
	v_sub_f32_e32 v21, v21, v247
	v_sub_f32_e32 v6, v6, v247
	v_sub_f32_e32 v22, v22, v247
	v_sub_f32_e32 v7, v7, v247
	v_sub_f32_e32 v23, v23, v247
	v_sub_f32_e32 v8, v8, v247
	v_sub_f32_e32 v24, v24, v247
	v_sub_f32_e32 v9, v9, v247
	v_sub_f32_e32 v25, v25, v247
	v_sub_f32_e32 v10, v10, v247
	v_sub_f32_e32 v26, v26, v247
	v_sub_f32_e32 v11, v11, v247
	v_sub_f32_e32 v27, v27, v247
	v_sub_f32_e32 v12, v12, v247
	v_sub_f32_e32 v28, v28, v247
	v_sub_f32_e32 v13, v13, v247
	v_sub_f32_e32 v29, v29, v247
	v_sub_f32_e32 v14, v14, v247
	v_sub_f32_e32 v30, v30, v247
	v_sub_f32_e32 v15, v15, v247
	v_sub_f32_e32 v31, v31, v247
	v_exp_f32_e32 v98, v2
	v_exp_f32_e32 v99, v3
	v_exp_f32_e32 v100, v4
	v_exp_f32_e32 v101, v5
	v_exp_f32_e32 v102, v6
	v_exp_f32_e32 v103, v7
	v_exp_f32_e32 v104, v8
	v_exp_f32_e32 v105, v9
	v_exp_f32_e32 v106, v10
	v_exp_f32_e32 v107, v11
	v_exp_f32_e32 v108, v12
	v_exp_f32_e32 v109, v13
	v_exp_f32_e32 v110, v14
	v_exp_f32_e32 v111, v15
	v_exp_f32_e32 v80, v16
	v_exp_f32_e32 v81, v17
	v_exp_f32_e32 v82, v18
	v_exp_f32_e32 v83, v19
	v_exp_f32_e32 v84, v20
	v_exp_f32_e32 v85, v21
	v_exp_f32_e32 v86, v22
	v_exp_f32_e32 v87, v23
	v_exp_f32_e32 v88, v24
	v_exp_f32_e32 v89, v25
	v_exp_f32_e32 v90, v26
	v_exp_f32_e32 v91, v27
	v_exp_f32_e32 v92, v28
	v_exp_f32_e32 v93, v29
	v_exp_f32_e32 v94, v30
	v_exp_f32_e32 v95, v31
	s_waitcnt vmcnt(3) lgkmcnt(0)
	s_barrier
	v_and_b32_e32 v0, 3, v36
	s_andn2_b64 vcc, exec, s[54:55]
	v_lshlrev_b32_e32 v208, 4, v0
	s_cbranch_vccnz .LBB0_313
; template<int THRL> __device__ __forceinline__ void attn_unit(int b,int h,int qb,unsigned char*wsb,char*shm,float kmax,const int CMB,float lam){
;     ...
;   float l_reg=0.f;f32x16 o[2];o[0]=f32x16{};o[1]=f32x16{};f32x16 o2[2];o2[0]=f32x16{};o2[1]=f32x16{};const f32x16 negm=f32x16{};
;   const int qrel=wid*QBLK+r32;
;     ...
;   bool resc=false;
;     ...
;   f32x16 pA0,pA1,pB0,pB1;
;   int sl_prev=0,sl_cur=0,sl_next=SLOTB;
	s_lshl_b32 s1, s43, 6
	s_add_i32 s6, s79, s1
	s_lshr_b32 s4, s6, 7
	s_mov_b32 s5, s7
	s_lshl_b64 s[4:5], s[4:5], 8
	s_lshl_b64 s[36:37], s[68:69], 1
	s_add_u32 s4, s36, s4
	v_mov_b32_e32 v209, v221
	s_addc_u32 s5, s37, s5
	s_lshl_b32 s1, s95, 9
	v_lshl_add_u64 v[0:1], s[4:5], 0, v[208:209]
	s_and_b32 s1, s1, 0x18000
	s_lshl_b64 s[4:5], s[66:67], 1
	s_lshl_b64 s[36:37], s[6:7], 1
	v_lshl_or_b32 v2, v214, 11, s1
	s_add_u32 s1, s64, s36
	s_addc_u32 s6, s65, s37
	v_mov_b32_e32 v3, v221
	s_add_u32 s4, s1, s4
	v_lshl_add_u64 v[0:1], v[0:1], 0, v[2:3]
	s_addc_u32 s5, s6, s5
	v_mov_b32_e32 v64, 0
	s_mov_b32 s33, 6
	v_lshl_add_u64 v[210:211], s[64:65], 0, v[0:1]
	v_lshl_add_u64 v[212:213], s[4:5], 0, v[220:221]
	s_movk_i32 s36, 0x4000
	s_movk_i32 s42, 0x2000
	s_mov_b32 s5, 0
	v_mov_b32_e32 v0, 0
	v_mov_b32_e32 v1, v64
	v_mov_b32_e32 v2, v64
	v_mov_b32_e32 v3, v64
	v_mov_b32_e32 v4, v64
	v_mov_b32_e32 v5, v64
	v_mov_b32_e32 v6, v64
	v_mov_b32_e32 v7, v64
	v_mov_b32_e32 v8, v64
	v_mov_b32_e32 v9, v64
	v_mov_b32_e32 v10, v64
	v_mov_b32_e32 v11, v64
	v_mov_b32_e32 v12, v64
	v_mov_b32_e32 v13, v64
	v_mov_b32_e32 v14, v64
	v_mov_b32_e32 v15, v64
	v_mov_b32_e32 v16, 0
	v_mov_b32_e32 v17, v64
	v_mov_b32_e32 v18, v64
	v_mov_b32_e32 v19, v64
	v_mov_b32_e32 v20, v64
	v_mov_b32_e32 v21, v64
	v_mov_b32_e32 v22, v64
	v_mov_b32_e32 v23, v64
	v_mov_b32_e32 v24, v64
	v_mov_b32_e32 v25, v64
	v_mov_b32_e32 v26, v64
	v_mov_b32_e32 v27, v64
	v_mov_b32_e32 v28, v64
	v_mov_b32_e32 v29, v64
	v_mov_b32_e32 v30, v64
	v_mov_b32_e32 v31, v64
	v_mov_b32_e32 v32, 0
	v_mov_b32_e32 v33, v64
	v_mov_b32_e32 v34, v64
	v_mov_b32_e32 v35, v64
	v_mov_b32_e32 v36, v64
	v_mov_b32_e32 v37, v64
	v_mov_b32_e32 v38, v64
	v_mov_b32_e32 v39, v64
	v_mov_b32_e32 v40, v64
	v_mov_b32_e32 v41, v64
	v_mov_b32_e32 v42, v64
	v_mov_b32_e32 v43, v64
	v_mov_b32_e32 v44, v64
	v_mov_b32_e32 v45, v64
	v_mov_b32_e32 v46, v64
	v_mov_b32_e32 v47, v64
	v_mov_b32_e32 v48, 0
	v_mov_b32_e32 v49, v64
	v_mov_b32_e32 v50, v64
	v_mov_b32_e32 v51, v64
	v_mov_b32_e32 v52, v64
	v_mov_b32_e32 v53, v64
	v_mov_b32_e32 v54, v64
	v_mov_b32_e32 v55, v64
	v_mov_b32_e32 v56, v64
	v_mov_b32_e32 v57, v64
	v_mov_b32_e32 v58, v64
	v_mov_b32_e32 v59, v64
	v_mov_b32_e32 v60, v64
	v_mov_b32_e32 v61, v64
	v_mov_b32_e32 v62, v64
	v_mov_b32_e32 v63, v64
	v_lshlrev_b32_e32 v143, 2, v230
	v_add_u32_e32 v143, 0x12800, v143
	ds_write_b32 v143, v246 offset:32768
	ds_write_b32 v143, v230
	ds_write_b32 v143, v231 offset:2048
	ds_write_b32 v143, v232 offset:4096
	ds_write_b32 v143, v233 offset:6144
	ds_write_b32 v143, v234 offset:8192
	ds_write_b32 v143, v235 offset:10240
	ds_write_b32 v143, v236 offset:12288
	ds_write_b32 v143, v237 offset:14336
	ds_write_b32 v143, v238 offset:16384
	ds_write_b32 v143, v239 offset:18432
	ds_write_b32 v143, v240 offset:20480
	ds_write_b32 v143, v241 offset:22528
	ds_write_b32 v143, v242 offset:24576
	ds_write_b32 v143, v243 offset:26624
	ds_write_b32 v143, v244 offset:28672
	ds_write_b32 v143, v245 offset:30720
	v_mov_b32_e32 v246, v143
	v_xor_b32_e32 v230, 0x80000000, v247
	v_mov_b32_e32 v231, v230
	v_mov_b32_e32 v232, v230
	v_mov_b32_e32 v233, v230
	v_mov_b32_e32 v234, v230
	v_mov_b32_e32 v235, v230
	v_mov_b32_e32 v236, v230
	v_mov_b32_e32 v237, v230
	v_mov_b32_e32 v238, v230
	v_mov_b32_e32 v239, v230
	v_mov_b32_e32 v240, v230
	v_mov_b32_e32 v241, v230
	v_mov_b32_e32 v242, v230
	v_mov_b32_e32 v243, v230
	v_mov_b32_e32 v244, v230
	v_mov_b32_e32 v245, v230
	s_waitcnt lgkmcnt(0)
	s_nop 0
	s_nop 0
	s_nop 0
	s_nop 0
	s_nop 0
	s_nop 0
.LBB0_311:
	s_mov_b32 s37, s36
	s_mov_b32 s4, s33
	s_mov_b32 s1, s42
	v_add_u32_e32 v209, s5, v252
	ds_read_b64_tr_b16 v[216:217], v209 offset:24576
	ds_read_b64_tr_b16 v[218:219], v209 offset:25088
	v_add_f32_e32 v65, v96, v97
	v_add_f32_e32 v65, v98, v65
	v_add_f32_e32 v65, v99, v65
	v_add_f32_e32 v65, v100, v65
	v_add_f32_e32 v65, v101, v65
	v_cvt_pk_bf16_f32 v172, v96, v97
	v_cvt_pk_bf16_f32 v173, v98, v99
	s_waitcnt lgkmcnt(9)
	v_mfma_f32_32x32x16_bf16 v[128:143], v[204:207], v[156:159], v[230:245]
	ds_read_b64_tr_b16 v[204:205], v209 offset:28672
	ds_read_b64_tr_b16 v[206:207], v209 offset:29184
	v_add_f32_e32 v65, v102, v65
	v_add_f32_e32 v65, v103, v65
	v_add_f32_e32 v65, v104, v65
	v_add_f32_e32 v65, v105, v65
	v_cvt_pk_bf16_f32 v174, v100, v101
	v_cvt_pk_bf16_f32 v175, v102, v103
	s_waitcnt lgkmcnt(10)
	v_mfma_f32_32x32x16_bf16 v[112:127], v[200:203], v[156:159], v[230:245]
	ds_read_b64_tr_b16 v[74:75], v209 offset:25600
	ds_read_b64_tr_b16 v[76:77], v209 offset:26112
	v_add_f32_e32 v65, v106, v65
	v_add_f32_e32 v65, v107, v65
	v_add_f32_e32 v65, v108, v65
	v_add_f32_e32 v65, v109, v65
	v_cvt_pk_bf16_f32 v168, v104, v105
	v_cvt_pk_bf16_f32 v169, v106, v107
	s_waitcnt lgkmcnt(11)
	v_mfma_f32_32x32x16_bf16 v[128:143], v[196:199], v[152:155], v[128:143]
	ds_read_b64_tr_b16 v[70:71], v209 offset:29696
	ds_read_b64_tr_b16 v[72:73], v209 offset:30208
	v_add_f32_e32 v65, v110, v65
	v_add_f32_e32 v65, v111, v65
	v_add_f32_e32 v65, v80, v65
	v_add_f32_e32 v65, v81, v65
	v_cvt_pk_bf16_f32 v170, v108, v109
	v_cvt_pk_bf16_f32 v171, v110, v111
	s_waitcnt lgkmcnt(12)
	v_mfma_f32_32x32x16_bf16 v[112:127], v[192:195], v[152:155], v[112:127]
	ds_read_b64_tr_b16 v[66:67], v209 offset:26624
	ds_read_b64_tr_b16 v[68:69], v209 offset:27136
	v_add_f32_e32 v65, v82, v65
	v_add_f32_e32 v65, v83, v65
	v_add_f32_e32 v65, v84, v65
	v_add_f32_e32 v65, v85, v65
	v_cvt_pk_bf16_f32 v164, v80, v81
	v_cvt_pk_bf16_f32 v165, v82, v83
	s_waitcnt lgkmcnt(13)
	v_mfma_f32_32x32x16_bf16 v[128:143], v[188:191], v[148:151], v[128:143]
	ds_read_b64_tr_b16 v[100:101], v209 offset:30720
	ds_read_b64_tr_b16 v[102:103], v209 offset:31232
	v_add_f32_e32 v65, v86, v65
	v_add_f32_e32 v65, v87, v65
	v_add_f32_e32 v65, v88, v65
	v_add_f32_e32 v65, v89, v65
	v_cvt_pk_bf16_f32 v166, v84, v85
	v_cvt_pk_bf16_f32 v167, v86, v87
	s_waitcnt lgkmcnt(14)
	v_mfma_f32_32x32x16_bf16 v[112:127], v[184:187], v[148:151], v[112:127]
	ds_read_b64_tr_b16 v[96:97], v209 offset:27648
	ds_read_b64_tr_b16 v[98:99], v209 offset:28160
	v_add_f32_e32 v65, v90, v65
	v_add_f32_e32 v65, v91, v65
	v_add_f32_e32 v65, v92, v65
	v_add_f32_e32 v65, v93, v65
	v_cvt_pk_bf16_f32 v160, v88, v89
	v_cvt_pk_bf16_f32 v161, v90, v91
	s_waitcnt lgkmcnt(14)
	v_mfma_f32_32x32x16_bf16 v[128:143], v[180:183], v[144:147], v[128:143]
	ds_read_b64_tr_b16 v[86:87], v209 offset:31744
	ds_read_b64_tr_b16 v[88:89], v209 offset:32256
	v_add_f32_e32 v65, v94, v65
	v_add_f32_e32 v65, v95, v65
	v_add_f32_e32 v65, 0, v65
	v_cvt_pk_bf16_f32 v162, v92, v93
	v_cvt_pk_bf16_f32 v163, v94, v95
	v_mfma_f32_32x32x16_bf16 v[112:127], v[176:179], v[144:147], v[112:127]
	v_lshl_add_u64 v[190:191], v[212:213], 0, s[48:49]
	v_lshl_add_u64 v[78:79], v[190:191], 0, s[10:11]
	s_add_i32 s5, s42, s3
	s_mov_b32 s6, m0
	s_mov_b32 m0, s5
	s_nop 0
	global_load_lds_dwordx4 v[78:79], off
	s_mov_b32 m0, s6
	v_lshl_add_u64 v[188:189], v[210:211], 0, s[48:49]
	v_lshl_add_u64 v[78:79], v[188:189], 0, s[12:13]
	s_add_i32 s5, s36, s97
	s_mov_b32 s6, m0
	s_mov_b32 m0, s5
	s_nop 0
	global_load_lds_dwordx4 v[78:79], off
	s_mov_b32 m0, s6
	v_lshl_add_u64 v[78:79], v[188:189], 0, s[14:15]
	s_add_i32 s5, s36, s96
	s_mov_b32 s6, m0
	s_mov_b32 m0, s5
	s_nop 0
	global_load_lds_dwordx4 v[78:79], off
	s_mov_b32 m0, s6
	s_waitcnt lgkmcnt(14)
	v_mfma_f32_32x32x16_bf16 v[32:47], v[172:175], v[216:219], v[32:47]
	v_exp_f32_e32 v128, v128
	v_exp_f32_e32 v129, v129
	ds_read_b64_tr_b16 v[90:91], v209 offset:49152
	ds_read_b64_tr_b16 v[92:93], v209 offset:49664
	s_waitcnt lgkmcnt(14)
	v_mfma_f32_32x32x16_bf16 v[48:63], v[172:175], v[204:207], v[48:63]
	v_exp_f32_e32 v130, v130
	v_exp_f32_e32 v131, v131
	ds_read_b64_tr_b16 v[104:105], v209 offset:53248
	ds_read_b64_tr_b16 v[106:107], v209 offset:53760
	v_add_u32_e32 v94, s37, v250
	ds_read_b128 v[82:85], v94
	ds_read_b128 v[78:81], v94 offset:512
	s_waitcnt lgkmcnt(14)
	v_mfma_f32_32x32x16_bf16 v[32:47], v[168:171], v[74:77], v[32:47]
	v_exp_f32_e32 v132, v132
	v_exp_f32_e32 v133, v133
	ds_read_b64_tr_b16 v[108:109], v209 offset:50176
	ds_read_b64_tr_b16 v[110:111], v209 offset:50688
	ds_read_b128 v[184:187], v94 offset:2048
	ds_read_b128 v[176:179], v94 offset:2560
	v_mfma_f32_32x32x16_bf16 v[48:63], v[168:171], v[70:73], v[48:63]
	v_exp_f32_e32 v134, v134
	v_exp_f32_e32 v135, v135
	ds_read_b64_tr_b16 v[192:193], v209 offset:54272
	ds_read_b64_tr_b16 v[194:195], v209 offset:54784
	ds_read_b128 v[180:183], v94 offset:4096
	ds_read_b128 v[70:73], v94 offset:4608
	s_waitcnt lgkmcnt(14)
	v_mfma_f32_32x32x16_bf16 v[32:47], v[164:167], v[66:69], v[32:47]
	v_exp_f32_e32 v136, v136
	v_exp_f32_e32 v137, v137
	ds_read_b64_tr_b16 v[196:197], v209 offset:51200
	ds_read_b64_tr_b16 v[198:199], v209 offset:51712
	ds_read_b128 v[74:77], v94 offset:6144
	ds_read_b128 v[66:69], v94 offset:6656
	v_mfma_f32_32x32x16_bf16 v[48:63], v[164:167], v[100:103], v[48:63]
	v_exp_f32_e32 v138, v138
	v_exp_f32_e32 v139, v139
	ds_read_b64_tr_b16 v[100:101], v209 offset:55296
	ds_read_b64_tr_b16 v[102:103], v209 offset:55808
	v_mfma_f32_32x32x16_bf16 v[32:47], v[160:163], v[96:99], v[32:47]
	v_exp_f32_e32 v140, v140
	v_exp_f32_e32 v141, v141
	ds_read_b64_tr_b16 v[94:95], v209 offset:52224
	ds_read_b64_tr_b16 v[96:97], v209 offset:52736
	v_mfma_f32_32x32x16_bf16 v[48:63], v[160:163], v[86:89], v[48:63]
	v_exp_f32_e32 v142, v142
	v_exp_f32_e32 v143, v143
	ds_read_b64_tr_b16 v[86:87], v209 offset:56320
	ds_read_b64_tr_b16 v[88:89], v209 offset:56832
	s_waitcnt lgkmcnt(14)
	v_mfma_f32_32x32x16_bf16 v[0:15], v[172:175], v[90:93], v[0:15]
	v_exp_f32_e32 v112, v112
	v_exp_f32_e32 v113, v113
	v_mfma_f32_32x32x16_bf16 v[16:31], v[172:175], v[104:107], v[16:31]
	v_exp_f32_e32 v114, v114
	v_exp_f32_e32 v115, v115
	v_mfma_f32_32x32x16_bf16 v[0:15], v[168:171], v[108:111], v[0:15]
	v_exp_f32_e32 v116, v116
	v_exp_f32_e32 v117, v117
	s_waitcnt lgkmcnt(12)
	v_mfma_f32_32x32x16_bf16 v[16:31], v[168:171], v[192:195], v[16:31]
	v_exp_f32_e32 v118, v118
	v_exp_f32_e32 v119, v119
	s_waitcnt lgkmcnt(8)
	v_mfma_f32_32x32x16_bf16 v[0:15], v[164:167], v[196:199], v[0:15]
	v_exp_f32_e32 v120, v120
	v_exp_f32_e32 v121, v121
	s_waitcnt lgkmcnt(4)
	v_mfma_f32_32x32x16_bf16 v[16:31], v[164:167], v[100:103], v[16:31]
	v_exp_f32_e32 v122, v122
	v_exp_f32_e32 v123, v123
	s_waitcnt lgkmcnt(2)
	v_mfma_f32_32x32x16_bf16 v[0:15], v[160:163], v[94:97], v[0:15]
	v_exp_f32_e32 v124, v124
	v_exp_f32_e32 v125, v125
	s_waitcnt lgkmcnt(0)
	v_mfma_f32_32x32x16_bf16 v[16:31], v[160:163], v[86:89], v[16:31]
	v_exp_f32_e32 v126, v126
	v_exp_f32_e32 v127, v127
	s_waitcnt vmcnt(3) lgkmcnt(0)
	s_barrier
	s_add_i32 s5, s36, 0x2000
	s_cmpk_lg_i32 s36, 0x4000
	s_cselect_b32 s42, s5, 0
	v_add_u32_e32 v209, s1, v252
	ds_read_b64_tr_b16 v[192:193], v209 offset:24576
	ds_read_b64_tr_b16 v[194:195], v209 offset:25088
	v_mfma_f32_32x32x16_bf16 v[96:111], v[82:85], v[156:159], v[230:245]
	v_add_f32_e32 v86, v128, v129
	v_add_f32_e32 v86, v130, v86
	v_add_f32_e32 v86, v131, v86
	v_add_f32_e32 v86, v132, v86
	v_add_f32_e32 v86, v133, v86
	v_cvt_pk_bf16_f32 v172, v128, v129
	v_cvt_pk_bf16_f32 v173, v130, v131
	ds_read_b64_tr_b16 v[196:197], v209 offset:28672
	ds_read_b64_tr_b16 v[198:199], v209 offset:29184
	v_add_f32_e32 v82, v134, v86
	v_add_f32_e32 v82, v135, v82
	v_add_f32_e32 v82, v136, v82
	v_add_f32_e32 v128, v137, v82
	v_mfma_f32_32x32x16_bf16 v[80:95], v[78:81], v[156:159], v[230:245]
	v_cvt_pk_bf16_f32 v174, v132, v133
	v_cvt_pk_bf16_f32 v175, v134, v135
	ds_read_b64_tr_b16 v[216:217], v209 offset:25600
	ds_read_b64_tr_b16 v[218:219], v209 offset:26112
	v_mfma_f32_32x32x16_bf16 v[96:111], v[184:187], v[152:155], v[96:111]
	v_add_f32_e32 v78, v138, v128
	v_add_f32_e32 v78, v139, v78
	v_add_f32_e32 v78, v140, v78
	v_add_f32_e32 v78, v141, v78
	v_cvt_pk_bf16_f32 v168, v136, v137
	v_cvt_pk_bf16_f32 v169, v138, v139
	ds_read_b64_tr_b16 v[136:137], v209 offset:29696
	ds_read_b64_tr_b16 v[138:139], v209 offset:30208
	v_mfma_f32_32x32x16_bf16 v[80:95], v[176:179], v[152:155], v[80:95]
	v_add_f32_e32 v78, v142, v78
	v_add_f32_e32 v78, v143, v78
	v_add_f32_e32 v78, v112, v78
	v_add_f32_e32 v78, v113, v78
	v_cvt_pk_bf16_f32 v170, v140, v141
	v_cvt_pk_bf16_f32 v171, v142, v143
	ds_read_b64_tr_b16 v[132:133], v209 offset:26624
	ds_read_b64_tr_b16 v[134:135], v209 offset:27136
	v_mfma_f32_32x32x16_bf16 v[96:111], v[180:183], v[148:151], v[96:111]
	v_add_f32_e32 v78, v114, v78
	v_add_f32_e32 v78, v115, v78
	v_add_f32_e32 v78, v116, v78
	v_add_f32_e32 v78, v117, v78
	v_cvt_pk_bf16_f32 v164, v112, v113
	v_cvt_pk_bf16_f32 v165, v114, v115
	ds_read_b64_tr_b16 v[128:129], v209 offset:30720
	ds_read_b64_tr_b16 v[130:131], v209 offset:31232
	v_mfma_f32_32x32x16_bf16 v[80:95], v[70:73], v[148:151], v[80:95]
	v_add_f32_e32 v78, v118, v78
	v_add_f32_e32 v78, v119, v78
	v_add_f32_e32 v78, v120, v78
	v_add_f32_e32 v78, v121, v78
	v_cvt_pk_bf16_f32 v166, v116, v117
	v_cvt_pk_bf16_f32 v167, v118, v119
	ds_read_b64_tr_b16 v[112:113], v209 offset:27648
	ds_read_b64_tr_b16 v[114:115], v209 offset:28160
	v_mfma_f32_32x32x16_bf16 v[96:111], v[74:77], v[144:147], v[96:111]
	v_add_f32_e32 v70, v122, v78
	v_add_f32_e32 v70, v123, v70
	v_add_f32_e32 v70, v124, v70
	v_add_f32_e32 v78, v125, v70
	v_cvt_pk_bf16_f32 v160, v120, v121
	v_cvt_pk_bf16_f32 v161, v122, v123
	ds_read_b64_tr_b16 v[70:71], v209 offset:31744
	ds_read_b64_tr_b16 v[72:73], v209 offset:32256
	v_mfma_f32_32x32x16_bf16 v[80:95], v[66:69], v[144:147], v[80:95]
	v_add_f32_e32 v74, v126, v78
	v_add_f32_e32 v74, v127, v74
	v_add_f32_e32 v74, 0, v74
	v_cvt_pk_bf16_f32 v162, v124, v125
	v_cvt_pk_bf16_f32 v163, v126, v127
	v_lshl_add_u64 v[66:67], v[190:191], 0, s[16:17]
	s_add_i32 s1, s36, s3
	s_mov_b32 s5, m0
	s_mov_b32 m0, s1
	s_nop 0
	global_load_lds_dwordx4 v[66:67], off
	s_mov_b32 m0, s5
	v_lshl_add_u64 v[66:67], v[188:189], 0, s[18:19]
	s_add_i32 s1, s42, s97
	s_mov_b32 s5, m0
	s_mov_b32 m0, s1
	s_nop 0
	global_load_lds_dwordx4 v[66:67], off
	s_mov_b32 m0, s5
	v_lshl_add_u64 v[66:67], v[188:189], 0, s[20:21]
	s_add_i32 s1, s42, s96
	s_mov_b32 s5, m0
	s_mov_b32 m0, s1
	s_nop 0
	global_load_lds_dwordx4 v[66:67], off
	s_mov_b32 m0, s5
	s_waitcnt lgkmcnt(14)
	v_mfma_f32_32x32x16_bf16 v[32:47], v[172:175], v[192:195], v[32:47]
	v_exp_f32_e32 v96, v96
	v_exp_f32_e32 v97, v97
	ds_read_b64_tr_b16 v[66:67], v209 offset:49152
	ds_read_b64_tr_b16 v[68:69], v209 offset:49664
	s_waitcnt lgkmcnt(14)
	v_mfma_f32_32x32x16_bf16 v[48:63], v[172:175], v[196:199], v[48:63]
	v_exp_f32_e32 v98, v98
	v_exp_f32_e32 v99, v99
	ds_read_b64_tr_b16 v[76:77], v209 offset:53248
	ds_read_b64_tr_b16 v[78:79], v209 offset:53760
	v_add_u32_e32 v75, s42, v250
	ds_read_b128 v[204:207], v75
	ds_read_b128 v[200:203], v75 offset:512
	s_waitcnt lgkmcnt(14)
	v_mfma_f32_32x32x16_bf16 v[32:47], v[168:171], v[216:219], v[32:47]
	v_exp_f32_e32 v100, v100
	v_exp_f32_e32 v101, v101
	ds_read_b64_tr_b16 v[116:117], v209 offset:50176
	ds_read_b64_tr_b16 v[118:119], v209 offset:50688
	ds_read_b128 v[196:199], v75 offset:2048
	ds_read_b128 v[192:195], v75 offset:2560
	v_mfma_f32_32x32x16_bf16 v[48:63], v[168:171], v[136:139], v[48:63]
	v_exp_f32_e32 v102, v102
	v_exp_f32_e32 v103, v103
	ds_read_b64_tr_b16 v[120:121], v209 offset:54272
	ds_read_b64_tr_b16 v[122:123], v209 offset:54784
	ds_read_b128 v[188:191], v75 offset:4096
	ds_read_b128 v[184:187], v75 offset:4608
	s_waitcnt lgkmcnt(14)
	v_mfma_f32_32x32x16_bf16 v[32:47], v[164:167], v[132:135], v[32:47]
	v_exp_f32_e32 v104, v104
	v_exp_f32_e32 v105, v105
	ds_read_b64_tr_b16 v[124:125], v209 offset:51200
	ds_read_b64_tr_b16 v[126:127], v209 offset:51712
	ds_read_b128 v[180:183], v75 offset:6144
	ds_read_b128 v[176:179], v75 offset:6656
	v_mfma_f32_32x32x16_bf16 v[48:63], v[164:167], v[128:131], v[48:63]
	v_exp_f32_e32 v106, v106
	v_exp_f32_e32 v107, v107
	ds_read_b64_tr_b16 v[128:129], v209 offset:55296
	ds_read_b64_tr_b16 v[130:131], v209 offset:55808
	v_mfma_f32_32x32x16_bf16 v[32:47], v[160:163], v[112:115], v[32:47]
	v_exp_f32_e32 v108, v108
	v_exp_f32_e32 v109, v109
	ds_read_b64_tr_b16 v[112:113], v209 offset:52224
	ds_read_b64_tr_b16 v[114:115], v209 offset:52736
	v_mfma_f32_32x32x16_bf16 v[48:63], v[160:163], v[70:73], v[48:63]
	v_exp_f32_e32 v110, v110
	v_exp_f32_e32 v111, v111
	ds_read_b64_tr_b16 v[70:71], v209 offset:56320
	ds_read_b64_tr_b16 v[72:73], v209 offset:56832
	s_waitcnt lgkmcnt(14)
	v_mfma_f32_32x32x16_bf16 v[0:15], v[172:175], v[66:69], v[0:15]
	v_exp_f32_e32 v80, v80
	v_exp_f32_e32 v81, v81
	v_mfma_f32_32x32x16_bf16 v[16:31], v[172:175], v[76:79], v[16:31]
	v_exp_f32_e32 v82, v82
	v_exp_f32_e32 v83, v83
	v_mfma_f32_32x32x16_bf16 v[0:15], v[168:171], v[116:119], v[0:15]
	v_exp_f32_e32 v84, v84
	v_exp_f32_e32 v85, v85
	s_waitcnt lgkmcnt(12)
	v_mfma_f32_32x32x16_bf16 v[16:31], v[168:171], v[120:123], v[16:31]
	v_exp_f32_e32 v86, v86
	v_exp_f32_e32 v87, v87
	s_waitcnt lgkmcnt(8)
	v_mfma_f32_32x32x16_bf16 v[0:15], v[164:167], v[124:127], v[0:15]
	v_exp_f32_e32 v88, v88
	v_exp_f32_e32 v89, v89
	s_waitcnt lgkmcnt(4)
	v_mfma_f32_32x32x16_bf16 v[16:31], v[164:167], v[128:131], v[16:31]
	v_exp_f32_e32 v90, v90
	v_exp_f32_e32 v91, v91
	s_waitcnt lgkmcnt(2)
	v_mfma_f32_32x32x16_bf16 v[0:15], v[160:163], v[112:115], v[0:15]
	v_exp_f32_e32 v92, v92
	v_exp_f32_e32 v93, v93
	s_waitcnt lgkmcnt(0)
	v_mfma_f32_32x32x16_bf16 v[16:31], v[160:163], v[70:73], v[16:31]
	v_exp_f32_e32 v94, v94
	v_exp_f32_e32 v95, v95
	s_add_i32 s1, s42, 0x2000
	s_waitcnt vmcnt(3) lgkmcnt(0)
	s_barrier
; #define WAIT_BAR(N) asm volatile("s_waitcnt vmcnt(" #N ") lgkmcnt(0)\n\ts_barrier":::"memory")
;   #define RESC() do{ if(resc){ asm volatile("s_waitcnt lgkmcnt(0)":::"memory"); \
;       _Pragma("unroll") for(int d_=0;d_<2;++d_) _Pragma("unroll") for(int r=0;r<16;++r){const float f_=wsf[crow(r,hi)];o[d_][r]*=f_;o2[d_][r]*=f_;} } }while(0)
;   #define ROT() do{sl_prev=sl_cur;sl_cur=sl_next;sl_next=(sl_next==(NSLOT-1)*SLOTB)?0:sl_next+SLOTB;}while(0)
; template<int THRL> __device__ __forceinline__ void attn_unit(int b,int h,int qb,unsigned char*wsb,char*shm,float kmax,const int CMB,float lam){
;     ...
;   for(;t+5<NT;t+=2){
;     STEP(pB0,pB1,pA0,pA1,t,true,true,true);     WAIT_BAR(3); RESC(); ROT();
;     STEP(pA0,pA1,pB0,pB1,t+1,true,true,true);   WAIT_BAR(3); RESC(); ROT();
;   }
	s_cmpk_lg_i32 s42, 0x4000
	v_add_f32_e32 v64, v64, v65
	s_mov_b32 s5, s36
	s_cselect_b32 s36, s1, 0
	s_add_i32 s33, s33, 2
	v_lshl_add_u64 v[210:211], v[210:211], 0, s[22:23]
	v_lshl_add_u64 v[212:213], v[212:213], 0, s[22:23]
	s_cmp_ge_u32 s33, s89
	v_add_f32_e32 v64, v64, v74
	s_cbranch_scc0 .LBB0_311
	ds_read_b32 v230, v246
	ds_read_b32 v231, v246 offset:2048
	ds_read_b32 v232, v246 offset:4096
	ds_read_b32 v233, v246 offset:6144
	ds_read_b32 v234, v246 offset:8192
	ds_read_b32 v235, v246 offset:10240
	ds_read_b32 v236, v246 offset:12288
	ds_read_b32 v237, v246 offset:14336
	ds_read_b32 v238, v246 offset:16384
	ds_read_b32 v239, v246 offset:18432
	ds_read_b32 v240, v246 offset:20480
	ds_read_b32 v241, v246 offset:22528
	ds_read_b32 v242, v246 offset:24576
	ds_read_b32 v243, v246 offset:26624
	ds_read_b32 v244, v246 offset:28672
	ds_read_b32 v245, v246 offset:30720
	ds_read_b32 v246, v246 offset:32768
	s_waitcnt lgkmcnt(0)
	s_nop 0
	s_nop 0
	s_nop 0
	s_nop 0
	s_nop 0
	s_nop 0
	s_nop 0
	s_nop 0
	s_nop 0
	s_nop 0
	s_add_i32 s6, s4, -3
	s_branch .LBB0_314
